# mixer A: next query's Q fragments and index row loaded one query ahead
# baseline (speedup 1.0000x reference)
; DI void mixerA_item(const Params& p, int item, bf16* Ks, bf16* Vs, int lane) {
;   const bf16* PE = (const bf16*)(p.ws + WS_PE); bf16* Y = (bf16*)(p.ws + WS_Y);
;   const unsigned short* SEL = (const unsigned short*)(p.ws + WS_SEL) + (size_t)item * 256;
;   const int t = item & (SEQ - 1), b = item >> 13;
;   const int c = lane & 15, qd = lane >> 4, head = c & 7;
;   const size_t rowb = (size_t)b * SEQ;
;   const int count = (t + 1 < 256) ? t + 1 : 256, nsteps = (count + 31) >> 5;
;   bf16x8 qf[2];
; #pragma unroll
;   for (int ks = 0; ks < 2; ++ks) qf[ks] = *(const bf16x8*)(PE + (size_t)item * NPE + E_AQ + head * 64 + ks * 32 + qd * 8);
;   f32x4 o[4];
; #pragma unroll
;   for (int d = 0; d < 4; ++d) o[d] = (f32x4){0.f, 0.f, 0.f, 0.f};
;   float m = -1e30f, l = 0.f;
;   const bf16* Kg = PE + rowb * NPE + E_AK; const bf16* Vg = PE + rowb * NPE + E_AV;
;   KVRegs R;
;   unsigned short* sel_l = (unsigned short*)(Vs + 32 * WP);
; __global__ void __launch_bounds__(NTHREADS) fwd_kernel(Params p) {
;     ...
;   { FRESH_IDS
;     ...
;     const int nK = (2 * 2048 + (int)gridDim.x - 1) / (int)gridDim.x;
;     for (int rep = 0; rep < REP_AATT; ++rep)
;       for (int s2 = wid; s2 < nK * 4; s2 += 8) { const int it = SEL_ITEM(s2 >> 2); if (it < 2 * 2048) mixerA_item(p, (it >> 11) * SEQ + (it & 2047) * 4 + (s2 & 3), Ks, Vs, lane); }
.LBB0_2143:
	v_readlane_b32 s2, v254, 3
	v_readlane_b32 s3, v254, 4
	s_barrier
	s_load_dwordx2 s[0:1], s[2:3], 0x158
	v_mov_b32_e32 v0, v182
	s_waitcnt lgkmcnt(0)
	s_mov_b64 s[2:3], s[0:1]
	s_abs_i32 s0, s2
	v_cvt_f32_u32_e32 v1, s0
	s_sub_i32 s3, 0, s0
	s_add_i32 s1, s2, 0xfff
	s_xor_b32 s2, s1, s2
	v_rcp_iflag_f32_e32 v1, v1
	s_abs_i32 s1, s1
	s_ashr_i32 s2, s2, 31
	v_ashrrev_i32_e32 v73, 6, v0
	v_mul_f32_e32 v1, 0x4f7ffffe, v1
	v_cvt_u32_f32_e32 v1, v1
	s_nop 0
	v_readfirstlane_b32 s4, v1
	s_mul_i32 s3, s3, s4
	s_mul_hi_u32 s3, s4, s3
	s_add_i32 s4, s4, s3
	s_mul_hi_u32 s3, s1, s4
	s_mul_i32 s4, s3, s0
	s_sub_i32 s1, s1, s4
	s_add_i32 s4, s3, 1
	s_sub_i32 s5, s1, s0
	s_cmp_ge_u32 s1, s0
	s_cselect_b32 s3, s4, s3
	s_cselect_b32 s1, s5, s1
	s_add_i32 s4, s3, 1
	s_cmp_ge_u32 s1, s0
	s_cselect_b32 s0, s4, s3
	s_xor_b32 s0, s0, s2
	s_sub_i32 s0, s0, s2
	s_lshl_b32 s24, s0, 2
	v_cmp_gt_i32_e32 vcc, s24, v73
	s_and_saveexec_b64 s[0:1], vcc
	v_readlane_b32 s33, v254, 12
	s_cbranch_execz .LBB0_2171
	s_movk_i32 s2, 0x2600
	v_mul_lo_u32 v6, v73, s2
	v_readlane_b32 s2, v254, 3
	v_readlane_b32 s3, v254, 4
	s_load_dwordx2 s[2:3], s[2:3], 0xd0
	v_and_b32_e32 v1, 63, v0
	v_mov_b32_e32 v69, 0
	v_lshlrev_b32_e32 v2, 3, v1
	v_mov_b32_e32 v3, v69
	v_bfe_u32 v88, v0, 3, 3
	v_lshlrev_b32_e32 v1, 3, v0
	s_waitcnt lgkmcnt(0)
	v_lshl_add_u64 v[4:5], s[2:3], 0, v[2:3]
	v_and_b32_e32 v72, 56, v1
	v_mul_u32_u24_e32 v3, 0x48, v88
	v_add_u32_e32 v7, 0, v6
	v_lshlrev_b32_e32 v1, 1, v72
	v_lshlrev_b32_e32 v3, 1, v3
	v_add3_u32 v93, v7, v1, v3
	v_and_b32_e32 v1, 15, v0
	v_bfe_u32 v8, v0, 4, 2
	v_mul_u32_u24_e32 v1, 0x90, v1
	v_and_b32_e32 v3, 48, v0
	v_add3_u32 v94, v7, v1, v3
	v_lshlrev_b32_e32 v74, 2, v8
	v_bfe_u32 v1, v0, 2, 2
	v_or_b32_e32 v1, v74, v1
	v_add_u32_e32 v75, v7, v2
	v_mul_u32_u24_e32 v1, 0x90, v1
	v_and_b32_e32 v2, 24, v2
	v_add3_u32 v102, v7, v1, v2
	v_lshlrev_b32_e32 v1, 7, v0
	v_and_b32_e32 v2, 0x380, v1
	v_mov_b32_e32 v3, v69
	v_lshlrev_b32_e32 v68, 3, v8
	s_mov_b64 s[4:5], 0xda00000
	v_lshl_add_u64 v[76:77], s[2:3], 0, v[2:3]
	v_and_b32_e32 v9, 8, v0
	v_lshl_add_u64 v[70:71], v[4:5], 0, s[4:5]
	v_lshlrev_b32_e32 v4, 1, v88
	v_bfe_u32 v103, v0, 6, 2
	v_lshl_add_u64 v[0:1], v[76:77], 0, v[68:69]
	s_mov_b64 s[6:7], 0xa000000
	v_lshl_add_u64 v[78:79], v[0:1], 0, s[6:7]
	v_or_b32_e32 v0, v6, v4
	v_add_u32_e32 v0, 0, v0
	v_add_u32_e32 v89, v7, v4
	v_or_b32_e32 v90, 8, v88
	v_or_b32_e32 v91, 16, v88
	v_or_b32_e32 v92, 24, v88
	v_or_b32_e32 v95, 16, v74
	v_or_b32_e32 v96, 1, v74
	v_or_b32_e32 v97, 17, v74
	v_or_b32_e32 v98, 2, v74
	v_or_b32_e32 v99, 18, v74
	v_or_b32_e32 v100, 3, v74
	v_or_b32_e32 v101, 19, v74
	v_cmp_eq_u32_e64 s[4:5], 0, v9
	v_add_u32_e32 v104, 0x2440, v0
	v_or_b32_e32 v105, 56, v88
	s_mov_b64 s[18:19], 0
	v_mov_b32_e32 v106, s15
	v_mov_b32_e32 v107, s33
	s_movk_i32 s25, 0x1000
	s_movk_i32 s26, 0x1fff
	s_movk_i32 s27, 0x1800
	v_lshlrev_b32_e32 v80, 1, v68
	s_mov_b32 s28, 0x3000000
	s_mov_b32 s29, 0xff800000
	s_mov_b32 s30, 0x3e38aa3b
	v_mov_b32_e32 v108, 0xff800000
	s_mov_b32 s36, 0
	s_mov_b64 s[38:39], 0xc00000
	s_mov_b64 s[40:41], 0x100000
	s_branch .LBB0_2146

; DI void lds_fence() { asm volatile("s_waitcnt lgkmcnt(0)" ::: "memory"); __builtin_amdgcn_wave_barrier(); }
; #define A_LOAD(j) do { _Pragma("unroll") for (int i = 0; i < 4; ++i) { const int row = (lane >> 3) + 8 * i, ch = lane & 7, e = 32 * (j) + row; \
;       const int tokk = (e < count) ? (int)sel_l[e] : 0; const size_t off = (size_t)tokk * NPE + ch * 8; R.k[i] = *(const u32x4*)(Kg + off); R.v[i] = *(const u32x4*)(Vg + off); } } while (0)
; DI void mixerA_item(const Params& p, int item, bf16* Ks, bf16* Vs, int lane) {
;   const bf16* PE = (const bf16*)(p.ws + WS_PE); bf16* Y = (bf16*)(p.ws + WS_Y);
;   const unsigned short* SEL = (const unsigned short*)(p.ws + WS_SEL) + (size_t)item * 256;
;   const int t = item & (SEQ - 1), b = item >> 13;
;   const int c = lane & 15, qd = lane >> 4, head = c & 7;
;   const size_t rowb = (size_t)b * SEQ;
;   const int count = (t + 1 < 256) ? t + 1 : 256, nsteps = (count + 31) >> 5;
;   bf16x8 qf[2];
; #pragma unroll
;   for (int ks = 0; ks < 2; ++ks) qf[ks] = *(const bf16x8*)(PE + (size_t)item * NPE + E_AQ + head * 64 + ks * 32 + qd * 8);
;   f32x4 o[4];
; #pragma unroll
;   for (int d = 0; d < 4; ++d) o[d] = (f32x4){0.f, 0.f, 0.f, 0.f};
;   float m = -1e30f, l = 0.f;
;   const bf16* Kg = PE + rowb * NPE + E_AK; const bf16* Vg = PE + rowb * NPE + E_AV;
;   KVRegs R;
;   unsigned short* sel_l = (unsigned short*)(Vs + 32 * WP);
;   lds_fence();
;   *(u32x2*)(sel_l + 4 * lane) = *(const u32x2*)(SEL + 4 * lane);
;   lds_fence();
;     ...
;   A_LOAD(0);
;   for (int j = 0; j < nsteps; ++j) {
;     lds_fence();
;     kv_store(R, Ks, Vs, lane);
;     lds_fence();
;     if (j + 1 < nsteps) A_LOAD(j + 1);
.LBB0_2146:
	v_readlane_b32 s8, v254, 3
	v_readlane_b32 s9, v254, 4
	s_load_dwordx2 s[6:7], s[8:9], 0x158
	v_and_b32_e32 v0, 4, v73
	v_cmp_eq_u32_e32 vcc, 0, v0
	s_waitcnt lgkmcnt(0)
	v_ashrrev_i32_e32 v1, 2, v73
	v_cndmask_b32_e32 v0, v106, v107, vcc
	s_waitcnt lgkmcnt(0)
	v_mad_u64_u32 v[8:9], s[6:7], v1, s6, v[0:1]
	v_cmp_gt_i32_e32 vcc, s25, v8
	s_and_saveexec_b64 s[20:21], vcc
	s_cbranch_execz .LBB0_2145
	v_lshlrev_b32_e32 v9, 2, v8
	v_or_b32_e32 v82, v9, v103
	v_ashrrev_i32_e32 v83, 31, v82
	v_lshlrev_b64 v[10:11], 9, v[82:83]
	v_mad_i64_i32 v[84:85], s[6:7], v82, s27, v[76:77]
	v_mov_b32_e32 v81, v69
	v_lshl_add_u64 v[12:13], v[84:85], 0, v[80:81]
	v_lshl_add_u64 v[10:11], v[70:71], 0, v[10:11]
	v_lshl_add_u64 v[142:143], v[12:13], 0, s[38:39]
	v_lshl_add_u64 v[144:145], v[10:11], 0, s[40:41]
	s_cmp_lg_u32 s36, 0
	s_cbranch_scc1 .La_pf_use
	global_load_dwordx4 v[0:3], v[12:13], off
	global_load_dwordx4 v[4:7], v[12:13], off offset:64
	s_waitcnt lgkmcnt(0)
	global_load_dwordx2 v[10:11], v[10:11], off
	s_branch .La_pf_join
.La_pf_use:
	s_waitcnt vmcnt(0) lgkmcnt(0)
	v_mov_b32_e32 v0, v132
	v_mov_b32_e32 v1, v133
	v_mov_b32_e32 v2, v134
	v_mov_b32_e32 v3, v135
	v_mov_b32_e32 v4, v136
	v_mov_b32_e32 v5, v137
	v_mov_b32_e32 v6, v138
	v_mov_b32_e32 v7, v139
	v_mov_b32_e32 v10, v140
	v_mov_b32_e32 v11, v141
.La_pf_join:
	v_bitop3_b32 v9, v9, s26, v103 bitop3:0xc8
	v_min_u32_e32 v81, 0xff, v9
	v_cmp_le_u32_e64 s[8:9], v88, v81
	v_cmp_le_u32_e64 s[10:11], v90, v81
	v_cmp_le_u32_e64 s[12:13], v91, v81
	v_cmp_le_u32_e64 s[14:15], v92, v81
	s_waitcnt vmcnt(0)
	v_readfirstlane_b32 s37, v73
	s_add_i32 s37, s37, 8
	s_cmp_lt_i32 s37, s24
	s_cselect_b32 s36, 1, 0
	s_cbranch_scc0 .La_pf_skip
	global_load_dwordx4 v[132:135], v[142:143], off
	global_load_dwordx4 v[136:139], v[142:143], off offset:64
	global_load_dwordx2 v[140:141], v[144:145], off
.La_pf_skip:
	ds_write_b64 v75, v[10:11] offset:9216
	s_waitcnt lgkmcnt(0)
	ds_read_u16 v240, v89 offset:9216
	ds_read_u16 v241, v89 offset:9232
	ds_read_u16 v242, v89 offset:9248
	ds_read_u16 v243, v89 offset:9264
	v_ashrrev_i32_e32 v11, 11, v8
	v_mov_b64_e32 v[8:9], s[2:3]
	v_mad_i64_i32 v[86:87], s[6:7], v11, s28, v[8:9]
	s_waitcnt lgkmcnt(0)
	v_mul_u32_u24_e32 v240, 0xc00, v240
	v_mul_u32_u24_e32 v241, 0xc00, v241
	v_mul_u32_u24_e32 v242, 0xc00, v242
	v_mul_u32_u24_e32 v243, 0xc00, v243
	v_cndmask_b32_e64 v240, 0, v240, s[8:9]
	v_cndmask_b32_e64 v241, 0, v241, s[10:11]
	v_cndmask_b32_e64 v242, 0, v242, s[12:13]
	v_cndmask_b32_e64 v243, 0, v243, s[14:15]
	v_or_b32_e32 v240, v240, v72
	v_or_b32_e32 v241, v241, v72
	v_or_b32_e32 v242, v242, v72
	v_or_b32_e32 v243, v243, v72
	v_lshlrev_b32_e32 v68, 1, v240
	v_lshl_add_u64 v[200:201], v[86:87], 0, v[68:69]
	v_lshlrev_b32_e32 v68, 1, v241
	v_lshl_add_u64 v[202:203], v[86:87], 0, v[68:69]
	v_lshlrev_b32_e32 v68, 1, v242
	v_lshl_add_u64 v[204:205], v[86:87], 0, v[68:69]
	v_lshlrev_b32_e32 v68, 1, v243
	v_lshl_add_u64 v[206:207], v[86:87], 0, v[68:69]
	global_load_dwordx4 v[20:23], v[200:201], off offset:1024
	global_load_dwordx4 v[24:27], v[200:201], off offset:1152
	global_load_dwordx4 v[28:31], v[202:203], off offset:1024
	global_load_dwordx4 v[32:35], v[202:203], off offset:1152
	global_load_dwordx4 v[40:43], v[204:205], off offset:1024
	global_load_dwordx4 v[44:47], v[204:205], off offset:1152
	global_load_dwordx4 v[52:55], v[206:207], off offset:1024
	global_load_dwordx4 v[48:51], v[206:207], off offset:1152
	v_add_u32_e32 v8, 32, v81
	v_mov_b32_e32 v109, 0
	v_add_u32_e32 v110, 1, v81
	v_lshrrev_b32_e32 v111, 5, v8
	v_mov_b32_e32 v114, 0xf149f2ca
	s_mov_b32 s31, 0
	s_mov_b64 s[22:23], 0
	v_mov_b32_e32 v112, v105
	v_mov_b32_e32 v113, v104
	v_mov_b32_e32 v36, 0
	v_mov_b32_e32 v37, v109
	v_mov_b32_e32 v38, v109
	v_mov_b32_e32 v39, v109
	v_mov_b32_e32 v8, 0
	v_mov_b32_e32 v9, v109
	v_mov_b32_e32 v10, v109
	v_mov_b32_e32 v11, v109
	v_mov_b32_e32 v12, v109
	v_mov_b32_e32 v13, v109
	v_mov_b32_e32 v14, v109
	v_mov_b32_e32 v15, v109
	v_mov_b32_e32 v16, v109
	v_mov_b32_e32 v17, v109
	v_mov_b32_e32 v18, v109
	v_mov_b32_e32 v19, v109
	v_mov_b32_e32 v56, v109
	v_mov_b32_e32 v57, v109
	v_mov_b32_e32 v58, v109
	v_mov_b32_e32 v59, v109
	v_readfirstlane_b32 s34, v111
	s_cmp_gt_u32 s34, 1
	s_cbranch_scc0 .La2_pro_done
	ds_read_u16 v240, v113
	ds_read_u16 v241, v113 offset:16
	ds_read_u16 v242, v113 offset:32
	ds_read_u16 v243, v113 offset:48
	v_add_u32_e32 v244, -24, v112
	v_add_u32_e32 v245, -16, v112
	v_add_u32_e32 v246, -8, v112
	v_mov_b32_e32 v247, v112
	v_cmp_le_u32_e64 s[8:9], v244, v81
	v_cmp_le_u32_e64 s[10:11], v245, v81
	v_cmp_le_u32_e64 s[12:13], v246, v81
	v_cmp_le_u32_e64 s[14:15], v247, v81
	s_waitcnt lgkmcnt(0)
	v_mul_u32_u24_e32 v240, 0xc00, v240
	v_mul_u32_u24_e32 v241, 0xc00, v241
	v_mul_u32_u24_e32 v242, 0xc00, v242
	v_mul_u32_u24_e32 v243, 0xc00, v243
	v_cndmask_b32_e64 v240, 0, v240, s[8:9]
	v_cndmask_b32_e64 v241, 0, v241, s[10:11]
	v_cndmask_b32_e64 v242, 0, v242, s[12:13]
	v_cndmask_b32_e64 v243, 0, v243, s[14:15]
	v_or_b32_e32 v240, v240, v72
	v_or_b32_e32 v241, v241, v72
	v_or_b32_e32 v242, v242, v72
	v_or_b32_e32 v243, v243, v72
	v_lshlrev_b32_e32 v68, 1, v240
	v_lshl_add_u64 v[200:201], v[86:87], 0, v[68:69]
	v_lshlrev_b32_e32 v68, 1, v241
	v_lshl_add_u64 v[202:203], v[86:87], 0, v[68:69]
	v_lshlrev_b32_e32 v68, 1, v242
	v_lshl_add_u64 v[204:205], v[86:87], 0, v[68:69]
	v_lshlrev_b32_e32 v68, 1, v243
	v_lshl_add_u64 v[206:207], v[86:87], 0, v[68:69]
	global_load_dwordx4 v[208:211], v[200:201], off offset:1024
	global_load_dwordx4 v[212:215], v[200:201], off offset:1152
	global_load_dwordx4 v[216:219], v[202:203], off offset:1024
	global_load_dwordx4 v[220:223], v[202:203], off offset:1152
	global_load_dwordx4 v[224:227], v[204:205], off offset:1024
	global_load_dwordx4 v[228:231], v[204:205], off offset:1152
	global_load_dwordx4 v[232:235], v[206:207], off offset:1024
	global_load_dwordx4 v[236:239], v[206:207], off offset:1152

; __device__ __forceinline__ unsigned xb_add(unsigned* p, unsigned v) { return __hip_atomic_fetch_add(p, v, __ATOMIC_RELAXED, __HIP_MEMORY_SCOPE_AGENT); }
; __device__ __forceinline__ void xcd_barrier(const XcdBarrier& b) {
;     ...
;             __builtin_amdgcn_fence(__ATOMIC_ACQUIRE, "agent");
;             xb_add(&bar[XB_XGEN(b.x)], 1u);
;             asm volatile("s_waitcnt vmcnt(0)" ::: "memory");
.LBB0_2573:
	s_or_b64 exec, exec, s[6:7]
	s_mov_b64 s[6:7], exec
	v_mbcnt_lo_u32_b32 v0, s6, 0
	v_mbcnt_hi_u32_b32 v0, s7, v0
	v_cmp_eq_u32_e32 vcc, 0, v0
	s_waitcnt vmcnt(0)
	buffer_inv sc1
	s_and_saveexec_b64 s[8:9], vcc
	s_cbranch_execz .LBB0_2575
	s_bcnt1_i32_b64 s6, s[6:7]
	v_mov_b32_e32 v0, 0x2000
	v_mov_b32_e32 v1, s6
	global_atomic_add v0, v1, s[2:3] offset:1024
	s_nop 0
	s_nop 0
	s_nop 0
	s_nop 0
	s_nop 0
	s_nop 0
	s_nop 0
	s_nop 0
	s_nop 0
	s_nop 0
	s_nop 0
	s_nop 0
	s_nop 0
	s_nop 0
	s_nop 0
	s_nop 0
	s_nop 0
	s_nop 0
	s_nop 0
	s_nop 0
	s_nop 0
	s_nop 0
	s_nop 0
	s_nop 0
	s_nop 0
	s_nop 0
	s_nop 0
	s_nop 0
	s_nop 0
	s_nop 0
	s_nop 0
	s_nop 0
	s_nop 0
	s_nop 0
	s_nop 0
	s_nop 0
	s_nop 0
	s_nop 0
	s_nop 0
	s_nop 0
	s_nop 0
	s_nop 0
	s_nop 0
	s_nop 0
	s_nop 0
	s_nop 0
	s_nop 0
	s_nop 0
	s_nop 0
